# P2 work queue: pop atomic issued one iteration ahead (result read at the next pop), removing one exposed atomic round trip per item
# baseline (speedup 1.0000x reference)
.LBB0_496:
	v_mov_b32_e32 v0, v136
	v_readlane_b32 s4, v253, 3
	v_ashrrev_i32_e32 v1, 31, v0
	v_lshlrev_b64 v[2:3], 2, v[0:1]
	v_readlane_b32 s10, v253, 9
	v_readlane_b32 s11, v253, 10
	v_readlane_b32 s12, v253, 11
	v_readlane_b32 s13, v253, 12
	v_lshl_add_u64 v[4:5], s[10:11], 0, v[2:3]
	v_add_co_u32_e32 v6, vcc, 0x1000, v4
	global_load_dword v73, v[4:5], off
	global_load_dword v77, v[4:5], off offset:2048
	v_addc_co_u32_e32 v7, vcc, 0, v5, vcc
	global_load_dword v98, v[6:7], off
	global_load_dword v99, v[6:7], off offset:2048
	v_add_co_u32_e32 v6, vcc, 0x2000, v4
	v_readlane_b32 s14, v253, 13
	s_nop 0
	v_addc_co_u32_e32 v7, vcc, 0, v5, vcc
	global_load_dword v100, v[6:7], off
	global_load_dword v101, v[6:7], off offset:2048
	v_add_co_u32_e32 v6, vcc, 0x3000, v4
	v_readlane_b32 s15, v253, 14
	s_nop 0
	v_addc_co_u32_e32 v7, vcc, 0, v5, vcc
	global_load_dword v102, v[6:7], off
	global_load_dword v103, v[6:7], off offset:2048
	v_add_co_u32_e32 v6, vcc, 0x4000, v4
	v_readlane_b32 s16, v253, 15
	s_nop 0
	v_addc_co_u32_e32 v7, vcc, 0, v5, vcc
	global_load_dword v104, v[6:7], off
	global_load_dword v105, v[6:7], off offset:2048
	v_add_co_u32_e32 v6, vcc, 0x5000, v4
	v_readlane_b32 s17, v253, 16
	s_nop 0
	v_addc_co_u32_e32 v7, vcc, 0, v5, vcc
	global_load_dword v106, v[6:7], off
	global_load_dword v107, v[6:7], off offset:2048
	v_add_co_u32_e32 v6, vcc, 0x6000, v4
	v_readlane_b32 s5, v253, 4
	s_nop 0
	v_addc_co_u32_e32 v7, vcc, 0, v5, vcc
	global_load_dword v108, v[6:7], off
	global_load_dword v109, v[6:7], off offset:2048
	v_add_co_u32_e32 v6, vcc, 0x7000, v4
	v_readlane_b32 s6, v253, 5
	s_nop 0
	v_addc_co_u32_e32 v7, vcc, 0, v5, vcc
	global_load_dword v110, v[6:7], off
	global_load_dword v111, v[6:7], off offset:2048
	v_add_co_u32_e32 v6, vcc, 0x8000, v4
	v_readlane_b32 s7, v253, 6
	s_nop 0
	v_addc_co_u32_e32 v7, vcc, 0, v5, vcc
	global_load_dword v112, v[6:7], off
	global_load_dword v113, v[6:7], off offset:2048
	v_add_co_u32_e32 v6, vcc, 0x9000, v4
	v_readlane_b32 s8, v253, 7
	s_nop 0
	v_addc_co_u32_e32 v7, vcc, 0, v5, vcc
	global_load_dword v114, v[6:7], off
	global_load_dword v115, v[6:7], off offset:2048
	v_add_co_u32_e32 v6, vcc, 0xa000, v4
	v_readlane_b32 s9, v253, 8
	s_nop 0
	v_addc_co_u32_e32 v7, vcc, 0, v5, vcc
	global_load_dword v116, v[6:7], off
	global_load_dword v117, v[6:7], off offset:2048
	v_add_co_u32_e32 v6, vcc, 0xb000, v4
	v_readlane_b32 s18, v253, 17
	s_nop 0
	v_addc_co_u32_e32 v7, vcc, 0, v5, vcc
	global_load_dword v118, v[6:7], off
	global_load_dword v119, v[6:7], off offset:2048
	v_add_co_u32_e32 v6, vcc, 0xc000, v4
	v_readlane_b32 s19, v253, 18
	s_nop 0
	v_addc_co_u32_e32 v7, vcc, 0, v5, vcc
	global_load_dword v120, v[6:7], off
	global_load_dword v121, v[6:7], off offset:2048
	v_add_co_u32_e32 v6, vcc, 0xd000, v4
	s_nop 1
	v_addc_co_u32_e32 v7, vcc, 0, v5, vcc
	global_load_dword v122, v[6:7], off
	global_load_dword v123, v[6:7], off offset:2048
	v_add_co_u32_e32 v6, vcc, 0xe000, v4
	s_nop 1
	v_addc_co_u32_e32 v7, vcc, 0, v5, vcc
	v_add_co_u32_e32 v4, vcc, 0xf000, v4
	global_load_dword v124, v[6:7], off
	global_load_dword v125, v[6:7], off offset:2048
	v_addc_co_u32_e32 v5, vcc, 0, v5, vcc
	global_load_dword v126, v[4:5], off
	v_lshl_add_u64 v[4:5], s[12:13], 0, v[2:3]
	global_load_dword v127, v[4:5], off
	v_lshl_add_u64 v[4:5], s[14:15], 0, v[2:3]
	v_lshl_add_u64 v[2:3], s[16:17], 0, v[2:3]
	global_load_dword v128, v[4:5], off
	global_load_dword v129, v[2:3], off
	s_barrier
	s_mov_b64 s[0:1], exec
	v_readlane_b32 s4, v253, 1
	v_readlane_b32 s5, v253, 2
	s_and_b64 s[4:5], s[0:1], s[4:5]
	s_mov_b64 exec, s[4:5]
	s_cbranch_execz .LBB0_500
	s_mov_b64 s[6:7], exec
	v_mbcnt_lo_u32_b32 v1, s6, 0
	v_mbcnt_hi_u32_b32 v1, s7, v1
	v_cmp_eq_u32_e32 vcc, 0, v1
	s_and_saveexec_b64 s[4:5], vcc
	s_cbranch_execz .LBB0_499
	s_bcnt1_i32_b64 s3, s[6:7]
	v_mov_b32_e32 v2, 0
	v_mov_b32_e32 v3, s3
	global_atomic_add v2, v2, v3, s[54:55] sc0
	v_mov_b32_e32 v251, 0
	v_mov_b32_e32 v250, 1
	global_atomic_add v250, v251, v250, s[54:55] sc0

.LBB0_504:
	s_barrier
	s_mov_b64 s[76:77], exec
	v_readlane_b32 s4, v253, 1
	v_readlane_b32 s5, v253, 2
	s_and_b64 s[4:5], s[76:77], s[4:5]
	s_mov_b64 exec, s[4:5]
	s_cbranch_execz .LBB0_508
	s_mov_b64 s[90:91], exec
	v_mbcnt_lo_u32_b32 v32, s90, 0
	v_mbcnt_hi_u32_b32 v32, s91, v32
	v_cmp_eq_u32_e32 vcc, 0, v32
	s_and_saveexec_b64 s[88:89], vcc
	s_cbranch_execz .LBB0_507
	s_waitcnt vmcnt(0)
	v_mov_b32_e32 v33, v250
	v_mov_b32_e32 v250, 1
	global_atomic_add v250, v251, v250, s[54:55] sc0
.LBB0_507:
	s_or_b64 exec, exec, s[88:89]
	v_readfirstlane_b32 s0, v33
	v_mov_b32_e32 v33, s3
	s_nop 0
	v_add_u32_e32 v32, s0, v32
	ds_write_b32 v33, v32
